# + e1: scan output pass loads the loop-invariant head-norm gains once per item instead of twice per chunk (removes two load->wait stalls per chunk)
# baseline (speedup 1.0000x reference)
; #define LAS __attribute__((address_space(3)))
; template <bool OUT>
; __device__ __forceinline__ void scan_item(LAS unsigned char* lds, unsigned char* ws, const float* hgn_l, int item, int tid_in, int wid, int lane_in) {
;     const int h = item / NSEG, seg = item % NSEG;
;     float* SEG = (float*)(ws + WS_SEG); float* DSEG = (float*)(ws + WS_DSEG);
;     const bf16* Qp = (const bf16*)(ws + WS_Q); const bf16* Vp = (const bf16*)(ws + WS_V); bf16* AOp = (bf16*)(ws + WS_AO); const bf16* ZGp = (const bf16*)(ws + WS_ZG);
;     LAS unsigned short* QD = (LAS unsigned short*)(lds + L_QD); LAS unsigned short* QS = (LAS unsigned short*)(lds + L_QS); LAS unsigned short* KS = (LAS unsigned short*)(lds + L_KS);
;     LAS float* TOT = (LAS float*)(lds + L_TOT); LAS float* DV = (LAS float*)(lds + L_DV); LAS float* RS = (LAS float*)(lds + L_RS);
;     for (int dir = 0; dir < 2; ++dir) {
;         if (OUT && dir == 1) __syncthreads();
;         int tid = tid_in, lane = lane_in;
;         asm volatile("" : "+v"(tid), "+v"(lane));
;         f32x16 S[2];
;         bf16* spb = (bf16*)SEG + (size_t)((h * 2 + dir) * NSEG + seg) * 16384;
;         {
;             const int r = lane & 31, hh = lane >> 5, kb = wid >> 1;
; #pragma unroll
;             for (int j = 0; j < 2; ++j) { const int vc = (2 * (wid & 1) + j) * 32 + r;
; #pragma unroll
;                 for (int g = 0; g < 4; ++g) {
;                     if (OUT) { const u32x2 w = *(const u32x2*)(spb + vc * 128 + kb * 32 + 8 * g + 4 * hh);
;                         S[j][4 * g] = __uint_as_float(w.x << 16); S[j][4 * g + 1] = __uint_as_float(w.x & 0xffff0000u); S[j][4 * g + 2] = __uint_as_float(w.y << 16); S[j][4 * g + 3] = __uint_as_float(w.y & 0xffff0000u); }
;                     else { S[j][4 * g] = 0.f; S[j][4 * g + 1] = 0.f; S[j][4 * g + 2] = 0.f; S[j][4 * g + 3] = 0.f; } } }
;         }
;         const unsigned short* LFp = (const unsigned short*)(ws + (dir ? WS_LB : WS_LF));
;         unsigned lraw[8], vraw[8], qraw[8];
;         float dsa = 0.f, dsb = 0.f;
;         const int es = dir ? -D : D;
;         {
;             const int c = seg * SEGCH + (dir ? SEGCH - 1 : 0);
;             const unsigned e0 = (unsigned)((c * 64 + (dir ? 63 - wid * 8 : wid * 8)) * D + h * 128 + 2 * lane);
; #pragma unroll
;             for (int i = 0; i < 8; ++i) lraw[i] = *(const unsigned*)(LFp + (e0 + (unsigned)(i * es)));
; #pragma unroll
.LBB0_364:
	v_mov_b32_e32 v113, v210
	v_mov_b32_e32 v114, v211
	v_lshlrev_b32_e32 v168, 3, v113
	v_and_b32_e32 v168, 0x78, v168
	v_lshlrev_b32_e32 v168, 2, v168
	v_mov_b32_e32 v169, 0
	v_lshl_add_u64 v[168:169], s[94:95], 0, v[168:169]
	global_load_dwordx4 v[160:163], v[168:169], off
	global_load_dwordx4 v[164:167], v[168:169], off offset:16
	s_add_i32 s52, s75, s26
	s_ashr_i32 s53, s52, 31
	v_lshlrev_b32_e32 v0, 7, v114
	s_xor_b64 s[44:45], s[96:97], -1
	s_lshl_b64 s[52:53], s[52:53], 15
	v_and_b32_e32 v10, 0xf80, v0
	v_ashrrev_i32_e32 v0, 3, v114
	s_add_u32 s52, s85, s52
	v_and_b32_e32 v0, -4, v0
	s_addc_u32 s53, s60, s53
	v_ashrrev_i32_e32 v1, 31, v0
	v_lshl_add_u64 v[0:1], v[0:1], 1, s[52:53]
	s_and_b64 s[52:53], s[96:97], exec
	s_mov_b32 s26, 0xaa00000
	s_cselect_b32 s26, s26, 0xca00000
	s_add_u32 s58, s30, s26
	s_addc_u32 s59, s31, 0
	s_and_b64 s[52:53], s[96:97], exec
	s_cselect_b32 s26, 0, 7
	s_cselect_b32 s73, s65, 0xfffffc00
	s_or_b32 s26, s26, s72
	s_and_b64 s[52:53], s[96:97], exec
	s_cselect_b32 s38, s54, s55
	v_or_b32_e32 v2, s76, v10
	s_lshl_b32 s93, s38, 10
	v_lshlrev_b32_e32 v192, 1, v2
	v_or_b32_e32 v10, s77, v10
	s_lshl_b32 s26, s26, 16
	s_add_i32 s93, s93, s92
	v_lshl_add_u64 v[2:3], v[0:1], 0, v[192:193]
	v_lshlrev_b32_e32 v192, 1, v10
	s_add_i32 s26, s93, s26
	v_lshl_add_u64 v[0:1], v[0:1], 0, v[192:193]
	v_lshl_add_u32 v192, v114, 1, s26
	v_lshlrev_b64 v[16:17], 1, v[192:193]
	v_add_u32_e32 v192, s73, v192
	v_lshlrev_b64 v[20:21], 1, v[192:193]
	v_add_u32_e32 v192, s73, v192
	v_lshlrev_b64 v[24:25], 1, v[192:193]
	v_add_u32_e32 v192, s73, v192
	v_lshlrev_b64 v[28:29], 1, v[192:193]
	v_add_u32_e32 v192, s73, v192
	s_waitcnt lgkmcnt(0)
	v_lshlrev_b64 v[32:33], 1, v[192:193]
	v_add_u32_e32 v192, s73, v192
	v_lshlrev_b64 v[36:37], 1, v[192:193]
	v_add_u32_e32 v192, s73, v192
	v_lshlrev_b64 v[40:41], 1, v[192:193]
	v_add_u32_e32 v192, s73, v192
	v_lshl_add_u64 v[18:19], s[58:59], 0, v[16:17]
	v_lshl_add_u64 v[22:23], s[58:59], 0, v[20:21]
	v_lshl_add_u64 v[26:27], s[58:59], 0, v[24:25]
	v_lshl_add_u64 v[30:31], s[58:59], 0, v[28:29]
	v_lshlrev_b64 v[44:45], 1, v[192:193]
	global_load_dwordx2 v[4:5], v[2:3], off
	global_load_dwordx2 v[6:7], v[2:3], off offset:16
	global_load_dwordx2 v[8:9], v[2:3], off offset:32
	s_nop 0
	global_load_dwordx2 v[2:3], v[2:3], off offset:48
	s_nop 0
	global_load_dwordx2 v[10:11], v[0:1], off
	global_load_dwordx2 v[12:13], v[0:1], off offset:16
	global_load_dwordx2 v[14:15], v[0:1], off offset:32
	s_nop 0
	global_load_dwordx2 v[0:1], v[0:1], off offset:48
	v_lshl_add_u64 v[34:35], s[58:59], 0, v[32:33]
	v_lshl_add_u64 v[38:39], s[58:59], 0, v[36:37]
	v_lshl_add_u64 v[42:43], s[58:59], 0, v[40:41]
	v_lshl_add_u64 v[46:47], s[58:59], 0, v[44:45]
	global_load_dword v115, v[18:19], off
	global_load_dword v116, v[22:23], off
	global_load_dword v117, v[26:27], off
	global_load_dword v118, v[30:31], off
	global_load_dword v119, v[34:35], off
	global_load_dword v120, v[38:39], off
	global_load_dword v121, v[42:43], off
	global_load_dword v122, v[46:47], off
	v_lshl_add_u64 v[18:19], s[78:79], 0, v[16:17]
	v_lshl_add_u64 v[22:23], s[78:79], 0, v[20:21]
	v_lshl_add_u64 v[26:27], s[78:79], 0, v[24:25]
	v_lshl_add_u64 v[30:31], s[78:79], 0, v[28:29]
	v_lshl_add_u64 v[16:17], s[28:29], 0, v[16:17]
	v_lshl_add_u64 v[34:35], s[78:79], 0, v[32:33]
	v_lshl_add_u64 v[38:39], s[78:79], 0, v[36:37]
	v_lshl_add_u64 v[42:43], s[78:79], 0, v[40:41]
	v_lshl_add_u64 v[46:47], s[78:79], 0, v[44:45]
	global_load_dword v123, v[18:19], off
	global_load_dword v124, v[22:23], off
	global_load_dword v125, v[26:27], off
	global_load_dword v126, v[30:31], off
	global_load_dword v127, v[34:35], off
	global_load_dword v128, v[38:39], off
	global_load_dword v129, v[42:43], off
	global_load_dword v130, v[46:47], off
	v_lshl_add_u64 v[18:19], s[28:29], 0, v[20:21]
	v_lshl_add_u64 v[20:21], s[28:29], 0, v[24:25]
	v_lshl_add_u64 v[22:23], s[28:29], 0, v[28:29]
	v_lshl_add_u64 v[24:25], s[28:29], 0, v[32:33]
	v_lshl_add_u64 v[26:27], s[28:29], 0, v[36:37]
	v_lshl_add_u64 v[28:29], s[28:29], 0, v[40:41]
	v_lshl_add_u64 v[30:31], s[28:29], 0, v[44:45]
	global_load_dword v131, v[16:17], off
	global_load_dword v132, v[18:19], off
	global_load_dword v133, v[20:21], off
	global_load_dword v134, v[22:23], off
	global_load_dword v135, v[24:25], off
	global_load_dword v136, v[26:27], off
	global_load_dword v137, v[28:29], off
	global_load_dword v138, v[30:31], off
	s_mov_b32 s38, 1
	s_mov_b32 s26, 6
	s_waitcnt vmcnt(0)
	v_lshlrev_b32_e32 v32, 16, v4
	v_and_b32_e32 v33, 0xffff0000, v4
	v_lshlrev_b32_e32 v34, 16, v5
	v_and_b32_e32 v35, 0xffff0000, v5
	v_lshlrev_b32_e32 v36, 16, v6
	v_and_b32_e32 v37, 0xffff0000, v6
	v_lshlrev_b32_e32 v38, 16, v7
	v_and_b32_e32 v39, 0xffff0000, v7
	v_lshlrev_b32_e32 v40, 16, v8
	v_and_b32_e32 v41, 0xffff0000, v8
	v_lshlrev_b32_e32 v42, 16, v9
	v_and_b32_e32 v43, 0xffff0000, v9
	v_lshlrev_b32_e32 v44, 16, v2
	v_and_b32_e32 v45, 0xffff0000, v2
	v_lshlrev_b32_e32 v46, 16, v3
	v_and_b32_e32 v47, 0xffff0000, v3
	v_lshlrev_b32_e32 v48, 16, v10
	v_and_b32_e32 v49, 0xffff0000, v10
	v_lshlrev_b32_e32 v50, 16, v11
	v_and_b32_e32 v51, 0xffff0000, v11
	v_lshlrev_b32_e32 v52, 16, v12
	v_and_b32_e32 v53, 0xffff0000, v12
	v_lshlrev_b32_e32 v54, 16, v13
	v_and_b32_e32 v55, 0xffff0000, v13
	v_lshlrev_b32_e32 v56, 16, v14
	v_and_b32_e32 v57, 0xffff0000, v14
	v_lshlrev_b32_e32 v58, 16, v15
	v_and_b32_e32 v59, 0xffff0000, v15
	v_lshlrev_b32_e32 v60, 16, v0
	v_and_b32_e32 v61, 0xffff0000, v0
	v_lshlrev_b32_e32 v62, 16, v1
	v_and_b32_e32 v63, 0xffff0000, v1

; #define LAS __attribute__((address_space(3)))
; template <bool OUT>
; __device__ __forceinline__ void scan_item(LAS unsigned char* lds, unsigned char* ws, const float* hgn_l, int item, int tid_in, int wid, int lane_in) {
;     ...
;             if (OUT) {
;                 LAS float* STG = (LAS float*)(lds + L_QS);
; #pragma unroll
;                 for (int i = 0; i < 16; ++i) STG[(otb * 32 + rowf(i, hh)) * LDSTG + ovc] = o[i];
;                 LBAR();
; #pragma unroll
;                 for (int j = 0; j < 2; ++j) {
;                     const int tau = ftau + 32 * j;
;                     f32x4 a = *(const LAS f32x4*)(STG + tau * LDSTG + fv0), b = *(const LAS f32x4*)(STG + tau * LDSTG + fv0 + 4);
;                     if (dir == 0) {
;                         st8bf(AOp + (unsigned)((tok0 + tau) * D + h * 128 + fv0), a, b);
;                     } else {
;                         f32x4 fa, fb, za, zb;
;                         { const u32x4 w = aoraw[j];
;                           fa[0] = __uint_as_float(w.x << 16); fa[1] = __uint_as_float(w.x & 0xffff0000u); fa[2] = __uint_as_float(w.y << 16); fa[3] = __uint_as_float(w.y & 0xffff0000u);
;                           fb[0] = __uint_as_float(w.z << 16); fb[1] = __uint_as_float(w.z & 0xffff0000u); fb[2] = __uint_as_float(w.w << 16); fb[3] = __uint_as_float(w.w & 0xffff0000u); }
;                         { const u32x4 w = zgraw[j];
;                           za[0] = __uint_as_float(w.x << 16); za[1] = __uint_as_float(w.x & 0xffff0000u); za[2] = __uint_as_float(w.y << 16); za[3] = __uint_as_float(w.y & 0xffff0000u);
;                           zb[0] = __uint_as_float(w.z << 16); zb[1] = __uint_as_float(w.z & 0xffff0000u); zb[2] = __uint_as_float(w.w << 16); zb[3] = __uint_as_float(w.w & 0xffff0000u); }
;                         a = a + fa; b = b + fb;
;                         float ss = (a[0] * a[0] + a[1] * a[1]) + (a[2] * a[2] + a[3] * a[3]) + (b[0] * b[0] + b[1] * b[1]) + (b[2] * b[2] + b[3] * b[3]);
;                         ss = row16_sum(ss);
;                         const float rstd = rsqrtf(ss * (1.f / 128.f) + EPS);
;                         const f32x4 g0 = *(const f32x4*)(hgn_l + h * 128 + fv0), g1 = *(const f32x4*)(hgn_l + h * 128 + fv0 + 4);
;                         st8bf(AOp + (unsigned)((tok0 + 63 - tau) * D + h * 128 + fv0), a * rstd * g0 * za, b * rstd * g1 * zb);
.LBB0_381:
	v_lshl_add_u32 v49, v140, 2, s47
	v_lshlrev_b32_e32 v48, 2, v48
	v_mul_lo_u32 v49, v49, s57
	v_add3_u32 v48, 0, v48, v49
	v_add_u32_e32 v49, 0x4400, v48
	s_nop 5
	ds_write2_b32 v49, v32, v33 offset1:132
	v_add_u32_e32 v32, 0x4800, v48
	ds_write2_b32 v32, v34, v35 offset0:8 offset1:140
	v_add_u32_e32 v32, 0x5400, v48
	ds_write2_b32 v32, v36, v37 offset0:32 offset1:164
	v_add_u32_e32 v32, 0x5800, v48
	ds_write2_b32 v32, v38, v39 offset0:40 offset1:172
	v_add_u32_e32 v32, 0x6400, v48
	ds_write2_b32 v32, v40, v41 offset0:64 offset1:196
	v_add_u32_e32 v32, 0x6800, v48
	ds_write2_b32 v32, v42, v43 offset0:72 offset1:204
	v_add_u32_e32 v32, 0x7400, v48
	ds_write2_b32 v32, v44, v45 offset0:96 offset1:228
	v_add_u32_e32 v32, 0x7800, v48
	v_lshlrev_b32_e32 v192, 2, v143
	ds_write2_b32 v32, v46, v47 offset0:104 offset1:236
	v_add_u32_e32 v32, 0, v192
	v_mul_lo_u32 v33, v141, s57
	s_waitcnt lgkmcnt(0)
	s_barrier
	v_add_u32_e32 v61, v32, v33
	ds_read_b128 v[36:39], v61 offset:17408
	ds_read_b128 v[32:35], v61 offset:17424
	v_lshl_add_u64 v[44:45], s[94:95], 0, v[192:193]
	s_or_b32 s62, s70, 63
	s_mov_b64 s[52:53], -1
	s_and_b64 vcc, exec, s[44:45]
	s_cbranch_vccz .LBB0_383
	s_waitcnt vmcnt(3)
	v_lshlrev_b32_e32 v40, 16, v96
	v_and_b32_e32 v41, 0xffff0000, v96
	v_lshlrev_b32_e32 v42, 16, v97
	v_and_b32_e32 v43, 0xffff0000, v97
	s_waitcnt lgkmcnt(1)
	v_pk_add_f32 v[58:59], v[36:37], v[40:41]
	v_pk_add_f32 v[62:63], v[38:39], v[42:43]
	v_lshlrev_b32_e32 v50, 16, v98
	v_and_b32_e32 v51, 0xffff0000, v98
	v_lshlrev_b32_e32 v52, 16, v99
	v_and_b32_e32 v53, 0xffff0000, v99
	v_pk_mul_f32 v[40:41], v[62:63], v[62:63]
	v_pk_mul_f32 v[42:43], v[58:59], v[58:59]
	s_waitcnt lgkmcnt(0)
	v_pk_add_f32 v[50:51], v[32:33], v[50:51]
	v_pk_add_f32 v[52:53], v[34:35], v[52:53]
	v_pk_mov_b32 v[64:65], v[42:43], v[40:41] op_sel:[1,0]
	v_mov_b32_e32 v43, v41
	v_pk_add_f32 v[40:41], v[64:65], v[42:43]
	v_pk_mul_f32 v[42:43], v[52:53], v[52:53]
	v_pk_mul_f32 v[64:65], v[50:51], v[50:51]
	v_mov_b32_e32 v66, v42
	v_mov_b32_e32 v67, v64
	v_mov_b32_e32 v64, v43
	v_pk_add_f32 v[42:43], v[66:67], v[64:65]
	v_add_f32_e32 v40, v40, v41
	v_add_f32_e32 v40, v43, v40
	v_add_f32_e32 v40, v42, v40
	s_waitcnt vmcnt(2)
	v_lshlrev_b32_e32 v54, 16, v100
	v_and_b32_e32 v55, 0xffff0000, v100
	v_add_f32_dpp v40, v40, v40 quad_perm:[1,0,3,2] row_mask:0xf bank_mask:0xf bound_ctrl:1
	v_lshlrev_b32_e32 v56, 16, v101
	v_and_b32_e32 v57, 0xffff0000, v101
	v_add_f32_dpp v40, v40, v40 quad_perm:[2,3,0,1] row_mask:0xf bank_mask:0xf bound_ctrl:1
	v_lshlrev_b32_e32 v46, 16, v102
	v_and_b32_e32 v47, 0xffff0000, v102
	v_add_f32_dpp v40, v40, v40 row_half_mirror row_mask:0xf bank_mask:0xf bound_ctrl:1
	v_lshlrev_b32_e32 v48, 16, v103
	v_and_b32_e32 v49, 0xffff0000, v103
	v_add_f32_dpp v40, v40, v40 row_mirror row_mask:0xf bank_mask:0xf bound_ctrl:1
	v_fmamk_f32 v40, v40, 0x3c000000, v223
	v_cmp_gt_f32_e32 vcc, s24, v40
	v_mul_f32_e32 v41, 0x4b800000, v40
	v_sub_u32_e32 v68, s62, v141
	v_cndmask_b32_e32 v40, v40, v41, vcc
	v_rsq_f32_e32 v40, v40
	v_lshl_add_u32 v192, v68, 10, v139
	v_lshl_add_u64 v[68:69], v[192:193], 1, s[80:81]
	s_mov_b64 s[52:53], 0
	v_mul_f32_e32 v41, 0x45800000, v40
	v_cndmask_b32_e32 v60, v40, v41, vcc
	v_pk_mul_f32 v[62:63], v[62:63], v[60:61] op_sel_hi:[1,0]
	v_pk_mul_f32 v[58:59], v[58:59], v[60:61] op_sel_hi:[1,0]
	v_pk_mul_f32 v[52:53], v[52:53], v[60:61] op_sel_hi:[1,0]
	v_pk_mul_f32 v[50:51], v[50:51], v[60:61] op_sel_hi:[1,0]
	v_pk_mul_f32 v[42:43], v[166:167], v[52:53]
	v_pk_mul_f32 v[58:59], v[160:161], v[58:59]
	v_pk_mul_f32 v[62:63], v[162:163], v[62:63]
	v_pk_mul_f32 v[40:41], v[164:165], v[50:51]
	v_pk_mul_f32 v[56:57], v[62:63], v[56:57]
	v_pk_mul_f32 v[54:55], v[58:59], v[54:55]
	v_pk_mul_f32 v[48:49], v[42:43], v[48:49]
	v_pk_mul_f32 v[42:43], v[40:41], v[46:47]
	v_cvt_pk_bf16_f32 v40, v54, v55
	v_cvt_pk_bf16_f32 v41, v56, v57
	v_cvt_pk_bf16_f32 v42, v42, v43
	v_cvt_pk_bf16_f32 v43, v48, v49
	global_store_dwordx4 v[68:69], v[40:43], off

; #define LAS __attribute__((address_space(3)))
; template <bool OUT>
; __device__ __forceinline__ void scan_item(LAS unsigned char* lds, unsigned char* ws, const float* hgn_l, int item, int tid_in, int wid, int lane_in) {
;     ...
;                 for (int j = 0; j < 2; ++j) {
;                     const int tau = ftau + 32 * j;
;                     f32x4 a = *(const LAS f32x4*)(STG + tau * LDSTG + fv0), b = *(const LAS f32x4*)(STG + tau * LDSTG + fv0 + 4);
;                     if (dir == 0) {
;                         st8bf(AOp + (unsigned)((tok0 + tau) * D + h * 128 + fv0), a, b);
;                     } else {
;                         f32x4 fa, fb, za, zb;
;                         { const u32x4 w = aoraw[j];
;                           fa[0] = __uint_as_float(w.x << 16); fa[1] = __uint_as_float(w.x & 0xffff0000u); fa[2] = __uint_as_float(w.y << 16); fa[3] = __uint_as_float(w.y & 0xffff0000u);
;                           fb[0] = __uint_as_float(w.z << 16); fb[1] = __uint_as_float(w.z & 0xffff0000u); fb[2] = __uint_as_float(w.w << 16); fb[3] = __uint_as_float(w.w & 0xffff0000u); }
;                         { const u32x4 w = zgraw[j];
;                           za[0] = __uint_as_float(w.x << 16); za[1] = __uint_as_float(w.x & 0xffff0000u); za[2] = __uint_as_float(w.y << 16); za[3] = __uint_as_float(w.y & 0xffff0000u);
;                           zb[0] = __uint_as_float(w.z << 16); zb[1] = __uint_as_float(w.z & 0xffff0000u); zb[2] = __uint_as_float(w.w << 16); zb[3] = __uint_as_float(w.w & 0xffff0000u); }
;                         a = a + fa; b = b + fb;
;                         float ss = (a[0] * a[0] + a[1] * a[1]) + (a[2] * a[2] + a[3] * a[3]) + (b[0] * b[0] + b[1] * b[1]) + (b[2] * b[2] + b[3] * b[3]);
;                         ss = row16_sum(ss);
;                         const float rstd = rsqrtf(ss * (1.f / 128.f) + EPS);
;                         const f32x4 g0 = *(const f32x4*)(hgn_l + h * 128 + fv0), g1 = *(const f32x4*)(hgn_l + h * 128 + fv0 + 4);
;                         st8bf(AOp + (unsigned)((tok0 + 63 - tau) * D + h * 128 + fv0), a * rstd * g0 * za, b * rstd * g1 * zb);
.LBB0_385:
	s_waitcnt lgkmcnt(1)
	ds_read_b128 v[36:39], v61 offset:34304
	s_waitcnt lgkmcnt(1)
	ds_read_b128 v[32:35], v61 offset:34320
	v_add_u32_e32 v64, 32, v141
	s_andn2_b64 vcc, exec, s[44:45]
	s_mov_b64 s[52:53], -1
	s_cbranch_vccnz .LBB0_387
	s_waitcnt vmcnt(2)
	v_lshlrev_b32_e32 v40, 16, v104
	v_and_b32_e32 v41, 0xffff0000, v104
	v_lshlrev_b32_e32 v42, 16, v105
	v_and_b32_e32 v43, 0xffff0000, v105
	s_waitcnt lgkmcnt(1)
	v_pk_add_f32 v[58:59], v[36:37], v[40:41]
	v_pk_add_f32 v[62:63], v[38:39], v[42:43]
	v_lshlrev_b32_e32 v50, 16, v106
	v_and_b32_e32 v51, 0xffff0000, v106
	v_lshlrev_b32_e32 v52, 16, v107
	v_and_b32_e32 v53, 0xffff0000, v107
	v_pk_mul_f32 v[40:41], v[62:63], v[62:63]
	v_pk_mul_f32 v[42:43], v[58:59], v[58:59]
	s_waitcnt lgkmcnt(0)
	v_pk_add_f32 v[50:51], v[32:33], v[50:51]
	v_pk_add_f32 v[52:53], v[34:35], v[52:53]
	v_pk_mov_b32 v[60:61], v[42:43], v[40:41] op_sel:[1,0]
	v_mov_b32_e32 v43, v41
	v_pk_add_f32 v[40:41], v[60:61], v[42:43]
	v_pk_mul_f32 v[42:43], v[52:53], v[52:53]
	v_pk_mul_f32 v[60:61], v[50:51], v[50:51]
	v_mov_b32_e32 v66, v42
	v_mov_b32_e32 v67, v60
	v_mov_b32_e32 v60, v43
	v_pk_add_f32 v[42:43], v[66:67], v[60:61]
	v_add_f32_e32 v40, v40, v41
	v_add_f32_e32 v40, v43, v40
	v_add_f32_e32 v40, v42, v40
	s_waitcnt vmcnt(1)
	v_lshlrev_b32_e32 v54, 16, v108
	v_and_b32_e32 v55, 0xffff0000, v108
	v_add_f32_dpp v40, v40, v40 quad_perm:[1,0,3,2] row_mask:0xf bank_mask:0xf bound_ctrl:1
	v_lshlrev_b32_e32 v56, 16, v109
	v_and_b32_e32 v57, 0xffff0000, v109
	v_add_f32_dpp v40, v40, v40 quad_perm:[2,3,0,1] row_mask:0xf bank_mask:0xf bound_ctrl:1
	v_lshlrev_b32_e32 v46, 16, v110
	v_and_b32_e32 v47, 0xffff0000, v110
	v_add_f32_dpp v40, v40, v40 row_half_mirror row_mask:0xf bank_mask:0xf bound_ctrl:1
	v_lshlrev_b32_e32 v48, 16, v111
	v_and_b32_e32 v49, 0xffff0000, v111
	v_add_f32_dpp v40, v40, v40 row_mirror row_mask:0xf bank_mask:0xf bound_ctrl:1
	v_fmamk_f32 v40, v40, 0x3c000000, v223
	v_cmp_gt_f32_e32 vcc, s24, v40
	v_mul_f32_e32 v41, 0x4b800000, v40
	s_mov_b64 s[52:53], 0
	v_cndmask_b32_e32 v40, v40, v41, vcc
	v_rsq_f32_e32 v40, v40
	s_nop 0
	v_mul_f32_e32 v41, 0x45800000, v40
	v_cndmask_b32_e32 v60, v40, v41, vcc
	v_pk_mul_f32 v[62:63], v[62:63], v[60:61] op_sel_hi:[1,0]
	v_pk_mul_f32 v[58:59], v[58:59], v[60:61] op_sel_hi:[1,0]
	v_pk_mul_f32 v[52:53], v[52:53], v[60:61] op_sel_hi:[1,0]
	v_pk_mul_f32 v[50:51], v[50:51], v[60:61] op_sel_hi:[1,0]
	v_sub_u32_e32 v44, s62, v64
	v_lshl_add_u32 v192, v44, 10, v139
	v_lshl_add_u64 v[44:45], v[192:193], 1, s[80:81]
	v_pk_mul_f32 v[40:41], v[164:165], v[50:51]
	v_pk_mul_f32 v[58:59], v[160:161], v[58:59]
	v_pk_mul_f32 v[62:63], v[162:163], v[62:63]
	v_pk_mul_f32 v[42:43], v[166:167], v[52:53]
	v_pk_mul_f32 v[56:57], v[62:63], v[56:57]
	v_pk_mul_f32 v[54:55], v[58:59], v[54:55]
	v_pk_mul_f32 v[48:49], v[42:43], v[48:49]
	v_pk_mul_f32 v[42:43], v[40:41], v[46:47]
	v_cvt_pk_bf16_f32 v40, v54, v55
	v_cvt_pk_bf16_f32 v41, v56, v57
	v_cvt_pk_bf16_f32 v42, v42, v43
	v_cvt_pk_bf16_f32 v43, v48, v49
	global_store_dwordx4 v[44:45], v[40:43], off
